# P10: epilogue top waits only for the early first-row loads (counted past the next unit's tile prefetch and the second row's loads)
# speedup vs baseline: 1.0090x; 1.0035x over previous
.LBB0_1363:
	s_lshl_b32 s1, s26, 8
	v_add_u32_e32 v148, s1, v1
	v_ashrrev_i32_e32 v149, 31, v148
	v_lshlrev_b64 v[146:147], 6, v[148:149]
	v_lshl_add_u64 v[146:147], s[12:13], 0, v[146:147]
	v_mov_b32_e32 v216, 0x2000
	v_mov_b32_e32 v217, 0
	v_lshl_add_u64 v[248:249], v[250:251], 0, v[216:217]
	global_load_dwordx4 v[200:203], v[248:249], off
	global_load_dwordx4 v[204:207], v[248:249], off offset:16
	global_load_dwordx4 v[208:211], v[248:249], off offset:32
	global_load_dwordx4 v[212:215], v[248:249], off offset:48
	s_waitcnt vmcnt(12)
	v_pk_add_f32 v[218:219], v[232:233], v[236:237]
	v_pk_add_f32 v[220:221], v[230:231], v[234:235]
	v_pk_add_f32 v[222:223], v[240:241], v[244:245]
	v_pk_add_f32 v[224:225], v[238:239], v[242:243]
	v_pk_add_f32 v[218:219], v[218:219], v[222:223]
	v_pk_add_f32 v[220:221], v[220:221], v[224:225]
	s_nop 0
	v_pk_mov_b32 v[222:223], v[220:221], v[218:219] op_sel:[1,0]
	v_mov_b32_e32 v221, v219
	v_pk_add_f32 v[220:221], v[222:223], v[220:221]
	s_nop 0
	v_add_f32_e32 v226, v220, v221
	v_mov_b32_e32 v227, v226
	s_nop 1
	v_permlane16_swap_b32_e32 v226, v227
	v_mov_b32_e32 v228, v226
	v_mov_b32_e32 v229, v227
	s_nop 1
	v_permlane32_swap_b32_e32 v226, v228
	v_permlane32_swap_b32_e32 v227, v229
	v_mov_b32_e32 v181, v116
	v_mov_b32_e32 v116, v125
	v_mov_b32_e32 v178, v126
	v_mov_b32_e32 v179, v118
	v_mov_b32_e32 v118, v127
	v_mov_b32_e32 v126, v128
	v_mov_b32_e32 v127, v120
	v_mov_b32_e32 v120, v129
	v_mov_b32_e32 v128, v122
	v_mov_b32_e32 v129, v114
	v_mov_b32_e32 v114, v123
	v_mov_b32_e32 v180, v124
	v_lshl_or_b32 v176, s0, 7, v154
	v_mov_b64_e32 v[146:147], s[10:11]
	v_ashrrev_i32_e32 v177, 31, v176
	v_add_u32_e32 v182, s1, v151
	v_mad_i64_i32 v[124:125], s[2:3], v148, s52, v[146:147]
	v_lshlrev_b64 v[122:123], 1, v[176:177]
	v_ashrrev_i32_e32 v183, 31, v182
	v_lshl_add_u64 v[124:125], v[124:125], 0, v[122:123]
	s_andn2_b64 vcc, exec, s[4:5]
	s_mov_b64 s[4:5], -1
	s_nop 0
	v_lshlrev_b64 v[162:163], 6, v[182:183]
	v_mov_b32_e32 v149, v226
	v_fmamk_f32 v149, v149, 0x3a800000, v158
	v_rsq_f32_e32 v160, v149
	v_lshl_add_u64 v[162:163], s[12:13], 0, v[162:163]
	v_pk_mul_f32 v[116:117], v[116:117], v[160:161] op_sel_hi:[1,0]
	v_pk_mul_f32 v[164:165], v[178:179], v[160:161] op_sel_hi:[1,0]
	v_pk_mul_f32 v[118:119], v[118:119], v[160:161] op_sel_hi:[1,0]
	v_pk_mul_f32 v[126:127], v[126:127], v[160:161] op_sel_hi:[1,0]
	v_pk_mul_f32 v[120:121], v[120:121], v[160:161] op_sel_hi:[1,0]
	v_pk_mul_f32 v[128:129], v[128:129], v[160:161] op_sel_hi:[1,0]
	v_pk_mul_f32 v[114:115], v[114:115], v[160:161] op_sel_hi:[1,0]
	v_pk_mul_f32 v[166:167], v[180:181], v[160:161] op_sel_hi:[1,0]
	v_mul_f32_e32 v171, 0xbfb8aa3b, v117
	v_mul_f32_e32 v149, 0xbfb8aa3b, v165
	v_mul_f32_e32 v159, 0xbfb8aa3b, v119
	v_mul_f32_e32 v160, 0xbfb8aa3b, v127
	v_mul_f32_e32 v161, 0xbfb8aa3b, v121
	v_mul_f32_e32 v168, 0xbfb8aa3b, v129
	v_mul_f32_e32 v169, 0xbfb8aa3b, v115
	v_mul_f32_e32 v170, 0xbfb8aa3b, v167
	v_exp_f32_e32 v171, v171
	v_exp_f32_e32 v149, v149
	v_exp_f32_e32 v159, v159
	v_exp_f32_e32 v160, v160
	v_exp_f32_e32 v161, v161
	v_exp_f32_e32 v168, v168
	v_exp_f32_e32 v169, v169
	v_exp_f32_e32 v170, v170
	v_add_f32_e32 v171, 1.0, v171
	v_add_f32_e32 v149, 1.0, v149
	v_add_f32_e32 v159, 1.0, v159
	v_add_f32_e32 v160, 1.0, v160
	v_add_f32_e32 v161, 1.0, v161
	v_add_f32_e32 v168, 1.0, v168
	v_add_f32_e32 v169, 1.0, v169
	v_add_f32_e32 v170, 1.0, v170
	v_rcp_f32_e32 v171, v171
	v_rcp_f32_e32 v149, v149
	v_rcp_f32_e32 v159, v159
	v_rcp_f32_e32 v160, v160
	v_rcp_f32_e32 v161, v161
	v_rcp_f32_e32 v168, v168
	v_rcp_f32_e32 v169, v169
	v_rcp_f32_e32 v170, v170
	v_mul_f32_e32 v117, v117, v171
	v_mul_f32_e32 v149, v165, v149
	v_mul_f32_e32 v119, v119, v159
	v_mul_f32_e32 v127, v127, v160
	v_mul_f32_e32 v121, v121, v161
	v_mul_f32_e32 v129, v129, v168
	v_mul_f32_e32 v115, v115, v169
	v_mul_f32_e32 v159, v167, v170
	v_mul_f32_e32 v117, v116, v117
	v_mul_f32_e32 v149, v164, v149
	v_mul_f32_e32 v118, v118, v119
	v_mul_f32_e32 v119, v126, v127
	v_mul_f32_e32 v120, v120, v121
	v_mul_f32_e32 v121, v128, v129
	v_mul_f32_e32 v126, v114, v115
	v_mul_f32_e32 v127, v166, v159
	v_cvt_pk_bf16_f32 v114, v149, v118
	v_cvt_pk_bf16_f32 v115, v119, v120
	v_cvt_pk_bf16_f32 v116, v121, v126
	v_cvt_pk_bf16_f32 v117, v127, v117
	global_store_dwordx4 v[124:125], v[114:117], off
	s_nop 0
	s_nop 0
	v_mov_b32_e32 v129, v102
	v_mov_b32_e32 v102, v111
	v_mov_b32_e32 v111, v104
	v_mov_b32_e32 v104, v113
	v_mov_b32_e32 v113, v98
	v_mov_b32_e32 v98, v107
	v_mov_b32_e32 v107, v100
	v_mov_b32_e32 v100, v109
	v_mov_b32_e32 v128, v110
	v_mov_b32_e32 v110, v112
	v_mov_b32_e32 v112, v106
	v_mov_b32_e32 v106, v108
	v_add_u32_e32 v164, s1, v152
	v_mad_i64_i32 v[108:109], s[2:3], v182, s52, v[146:147]
	v_ashrrev_i32_e32 v165, 31, v164
	v_lshl_add_u64 v[108:109], v[108:109], 0, v[122:123]
	s_nop 0
	v_lshlrev_b64 v[116:117], 6, v[164:165]
	v_mov_b32_e32 v114, v227
	v_fmamk_f32 v114, v114, 0x3a800000, v158
	v_rsq_f32_e32 v114, v114
	v_lshl_add_u64 v[116:117], s[12:13], 0, v[116:117]
	v_pk_mul_f32 v[100:101], v[100:101], v[114:115] op_sel_hi:[1,0]
	v_pk_mul_f32 v[118:119], v[128:129], v[114:115] op_sel_hi:[1,0]
	v_pk_mul_f32 v[102:103], v[102:103], v[114:115] op_sel_hi:[1,0]
	v_pk_mul_f32 v[110:111], v[110:111], v[114:115] op_sel_hi:[1,0]
	v_pk_mul_f32 v[104:105], v[104:105], v[114:115] op_sel_hi:[1,0]
	v_pk_mul_f32 v[112:113], v[112:113], v[114:115] op_sel_hi:[1,0]
	v_pk_mul_f32 v[98:99], v[98:99], v[114:115] op_sel_hi:[1,0]
	v_pk_mul_f32 v[106:107], v[106:107], v[114:115] op_sel_hi:[1,0]
	v_mul_f32_e32 v127, 0xbfb8aa3b, v101
	v_mul_f32_e32 v114, 0xbfb8aa3b, v119
	v_mul_f32_e32 v115, 0xbfb8aa3b, v103
	v_mul_f32_e32 v120, 0xbfb8aa3b, v111
	v_mul_f32_e32 v121, 0xbfb8aa3b, v105
	v_mul_f32_e32 v124, 0xbfb8aa3b, v113
	v_mul_f32_e32 v125, 0xbfb8aa3b, v99
	v_mul_f32_e32 v126, 0xbfb8aa3b, v107
	v_exp_f32_e32 v127, v127
	v_exp_f32_e32 v114, v114
	v_exp_f32_e32 v115, v115
	v_exp_f32_e32 v120, v120
	v_exp_f32_e32 v121, v121
	v_exp_f32_e32 v124, v124
	v_exp_f32_e32 v125, v125
	v_exp_f32_e32 v126, v126
	v_add_f32_e32 v127, 1.0, v127
	v_add_f32_e32 v114, 1.0, v114
	v_add_f32_e32 v115, 1.0, v115
	v_add_f32_e32 v120, 1.0, v120
	v_add_f32_e32 v121, 1.0, v121
	v_add_f32_e32 v124, 1.0, v124
	v_add_f32_e32 v125, 1.0, v125
	v_add_f32_e32 v126, 1.0, v126
	v_rcp_f32_e32 v127, v127
	v_rcp_f32_e32 v114, v114
	v_rcp_f32_e32 v115, v115
	v_rcp_f32_e32 v120, v120
	v_rcp_f32_e32 v121, v121
	v_rcp_f32_e32 v124, v124
	v_rcp_f32_e32 v125, v125
	v_rcp_f32_e32 v126, v126
	v_mul_f32_e32 v101, v101, v127
	v_mul_f32_e32 v114, v119, v114
	v_mul_f32_e32 v103, v103, v115
	v_mul_f32_e32 v111, v111, v120
	v_mul_f32_e32 v105, v105, v121
	v_mul_f32_e32 v113, v113, v124
	v_mul_f32_e32 v99, v99, v125
	v_mul_f32_e32 v107, v107, v126
	v_mul_f32_e32 v101, v100, v101
	v_mul_f32_e32 v114, v118, v114
	v_mul_f32_e32 v102, v102, v103
	v_mul_f32_e32 v103, v110, v111
	v_mul_f32_e32 v104, v104, v105
	v_mul_f32_e32 v105, v112, v113
	v_mul_f32_e32 v110, v98, v99
	v_mul_f32_e32 v106, v106, v107
	v_cvt_pk_bf16_f32 v98, v114, v102
	v_cvt_pk_bf16_f32 v99, v103, v104
	v_cvt_pk_bf16_f32 v100, v105, v110
	v_cvt_pk_bf16_f32 v101, v106, v101
	global_store_dwordx4 v[108:109], v[98:101], off
	s_nop 0
	v_mov_b32_e32 v115, v86
	v_mov_b32_e32 v86, v95
	v_mov_b32_e32 v95, v88
	v_mov_b32_e32 v88, v97
	v_mov_b32_e32 v97, v82
	v_mov_b32_e32 v82, v91
	v_mov_b32_e32 v91, v84
	v_mov_b32_e32 v84, v93
	v_mov_b32_e32 v114, v94
	v_mov_b32_e32 v94, v96
	v_mov_b32_e32 v96, v90
	v_mov_b32_e32 v90, v92
	v_add_u32_e32 v116, s1, v153
	v_mad_i64_i32 v[92:93], s[0:1], v164, s52, v[146:147]
	v_ashrrev_i32_e32 v117, 31, v116
	v_lshl_add_u64 v[92:93], v[92:93], 0, v[122:123]
	s_nop 0
	v_lshlrev_b64 v[100:101], 6, v[116:117]
	v_mov_b32_e32 v98, v228
	v_fmamk_f32 v98, v98, 0x3a800000, v158
	v_rsq_f32_e32 v98, v98
	v_lshl_add_u64 v[100:101], s[12:13], 0, v[100:101]
	v_pk_mul_f32 v[84:85], v[84:85], v[98:99] op_sel_hi:[1,0]
	v_pk_mul_f32 v[102:103], v[114:115], v[98:99] op_sel_hi:[1,0]
	v_pk_mul_f32 v[86:87], v[86:87], v[98:99] op_sel_hi:[1,0]
	v_pk_mul_f32 v[94:95], v[94:95], v[98:99] op_sel_hi:[1,0]
	v_pk_mul_f32 v[88:89], v[88:89], v[98:99] op_sel_hi:[1,0]
	v_pk_mul_f32 v[96:97], v[96:97], v[98:99] op_sel_hi:[1,0]
	v_pk_mul_f32 v[82:83], v[82:83], v[98:99] op_sel_hi:[1,0]
	v_pk_mul_f32 v[90:91], v[90:91], v[98:99] op_sel_hi:[1,0]
	v_mul_f32_e32 v109, 0xbfb8aa3b, v85
	v_mul_f32_e32 v98, 0xbfb8aa3b, v103
	v_mul_f32_e32 v99, 0xbfb8aa3b, v87
	v_mul_f32_e32 v104, 0xbfb8aa3b, v95
	v_mul_f32_e32 v105, 0xbfb8aa3b, v89
	v_mul_f32_e32 v106, 0xbfb8aa3b, v97
	v_mul_f32_e32 v107, 0xbfb8aa3b, v83
	v_mul_f32_e32 v108, 0xbfb8aa3b, v91
	v_exp_f32_e32 v109, v109
	v_exp_f32_e32 v98, v98
	v_exp_f32_e32 v99, v99
	v_exp_f32_e32 v104, v104
	v_exp_f32_e32 v105, v105
	v_exp_f32_e32 v106, v106
	v_exp_f32_e32 v107, v107
	v_exp_f32_e32 v108, v108
	v_add_f32_e32 v109, 1.0, v109
	v_add_f32_e32 v98, 1.0, v98
	v_add_f32_e32 v99, 1.0, v99
	v_add_f32_e32 v104, 1.0, v104
	v_add_f32_e32 v105, 1.0, v105
	v_add_f32_e32 v106, 1.0, v106
	v_add_f32_e32 v107, 1.0, v107
	v_add_f32_e32 v108, 1.0, v108
	v_rcp_f32_e32 v109, v109
	v_rcp_f32_e32 v98, v98
	v_rcp_f32_e32 v99, v99
	v_rcp_f32_e32 v104, v104
	v_rcp_f32_e32 v105, v105
	v_rcp_f32_e32 v106, v106
	v_rcp_f32_e32 v107, v107
	v_rcp_f32_e32 v108, v108
	v_mul_f32_e32 v85, v85, v109
	v_mul_f32_e32 v98, v103, v98
	v_mul_f32_e32 v87, v87, v99
	v_mul_f32_e32 v95, v95, v104
	v_mul_f32_e32 v89, v89, v105
	v_mul_f32_e32 v97, v97, v106
	v_mul_f32_e32 v83, v83, v107
	v_mul_f32_e32 v91, v91, v108
	v_mul_f32_e32 v85, v84, v85
	v_mul_f32_e32 v98, v102, v98
	v_mul_f32_e32 v86, v86, v87
	v_mul_f32_e32 v87, v94, v95
	v_mul_f32_e32 v88, v88, v89
	v_mul_f32_e32 v89, v96, v97
	v_mul_f32_e32 v94, v82, v83
	v_mul_f32_e32 v90, v90, v91
	v_cvt_pk_bf16_f32 v82, v98, v86
	v_cvt_pk_bf16_f32 v83, v87, v88
	v_cvt_pk_bf16_f32 v84, v89, v94
	v_cvt_pk_bf16_f32 v85, v90, v85
	global_store_dwordx4 v[92:93], v[82:85], off
	s_nop 0
	v_mov_b32_e32 v99, v70
	v_mov_b32_e32 v70, v79
	v_mov_b32_e32 v79, v72
	v_mov_b32_e32 v72, v81
	v_mov_b32_e32 v81, v66
	v_mov_b32_e32 v66, v75
	v_mov_b32_e32 v75, v68
	v_mov_b32_e32 v68, v77
	v_mov_b32_e32 v98, v78
	v_mov_b32_e32 v78, v80
	v_mov_b32_e32 v80, v74
	v_mov_b32_e32 v74, v76
	v_add_u32_e32 v100, 0x80, v148
	v_mad_i64_i32 v[76:77], s[0:1], v116, s52, v[146:147]
	v_ashrrev_i32_e32 v101, 31, v100
	v_lshl_add_u64 v[76:77], v[76:77], 0, v[122:123]
	s_nop 0
	v_lshlrev_b64 v[84:85], 6, v[100:101]
	v_mov_b32_e32 v82, v229
	v_fmamk_f32 v82, v82, 0x3a800000, v158
	v_rsq_f32_e32 v82, v82
	v_lshl_add_u64 v[84:85], s[12:13], 0, v[84:85]
	v_pk_mul_f32 v[68:69], v[68:69], v[82:83] op_sel_hi:[1,0]
	v_pk_mul_f32 v[86:87], v[98:99], v[82:83] op_sel_hi:[1,0]
	v_pk_mul_f32 v[70:71], v[70:71], v[82:83] op_sel_hi:[1,0]
	v_pk_mul_f32 v[78:79], v[78:79], v[82:83] op_sel_hi:[1,0]
	v_pk_mul_f32 v[72:73], v[72:73], v[82:83] op_sel_hi:[1,0]
	v_pk_mul_f32 v[80:81], v[80:81], v[82:83] op_sel_hi:[1,0]
	v_pk_mul_f32 v[66:67], v[66:67], v[82:83] op_sel_hi:[1,0]
	v_pk_mul_f32 v[74:75], v[74:75], v[82:83] op_sel_hi:[1,0]
	v_mul_f32_e32 v93, 0xbfb8aa3b, v69
	v_mul_f32_e32 v82, 0xbfb8aa3b, v87
	v_mul_f32_e32 v83, 0xbfb8aa3b, v71
	v_mul_f32_e32 v88, 0xbfb8aa3b, v79
	v_mul_f32_e32 v89, 0xbfb8aa3b, v73
	v_mul_f32_e32 v90, 0xbfb8aa3b, v81
	v_mul_f32_e32 v91, 0xbfb8aa3b, v67
	v_mul_f32_e32 v92, 0xbfb8aa3b, v75
	v_exp_f32_e32 v93, v93
	v_exp_f32_e32 v82, v82
	v_exp_f32_e32 v83, v83
	v_exp_f32_e32 v88, v88
	v_exp_f32_e32 v89, v89
	v_exp_f32_e32 v90, v90
	v_exp_f32_e32 v91, v91
	v_exp_f32_e32 v92, v92
	v_add_f32_e32 v93, 1.0, v93
	v_add_f32_e32 v82, 1.0, v82
	v_add_f32_e32 v83, 1.0, v83
	v_add_f32_e32 v88, 1.0, v88
	v_add_f32_e32 v89, 1.0, v89
	v_add_f32_e32 v90, 1.0, v90
	v_add_f32_e32 v91, 1.0, v91
	v_add_f32_e32 v92, 1.0, v92
	v_rcp_f32_e32 v93, v93
	v_rcp_f32_e32 v82, v82
	v_rcp_f32_e32 v83, v83
	v_rcp_f32_e32 v88, v88
	v_rcp_f32_e32 v89, v89
	v_rcp_f32_e32 v90, v90
	v_rcp_f32_e32 v91, v91
	v_rcp_f32_e32 v92, v92
	v_mul_f32_e32 v69, v69, v93
	v_mul_f32_e32 v82, v87, v82
	v_mul_f32_e32 v71, v71, v83
	v_mul_f32_e32 v79, v79, v88
	v_mul_f32_e32 v73, v73, v89
	v_mul_f32_e32 v81, v81, v90
	v_mul_f32_e32 v67, v67, v91
	v_mul_f32_e32 v75, v75, v92
	v_mul_f32_e32 v69, v68, v69
	v_mul_f32_e32 v82, v86, v82
	v_mul_f32_e32 v70, v70, v71
	v_mul_f32_e32 v71, v78, v79
	v_mul_f32_e32 v72, v72, v73
	v_mul_f32_e32 v73, v80, v81
	v_mul_f32_e32 v78, v66, v67
	v_mul_f32_e32 v74, v74, v75
	v_cvt_pk_bf16_f32 v66, v82, v70
	v_cvt_pk_bf16_f32 v67, v71, v72
	v_cvt_pk_bf16_f32 v68, v73, v78
	v_cvt_pk_bf16_f32 v69, v74, v69
	global_store_dwordx4 v[76:77], v[66:69], off
	s_nop 0
	v_mov_b32_e32 v83, v54
	v_mov_b32_e32 v54, v63
	v_mov_b32_e32 v63, v56
	v_mov_b32_e32 v56, v65
	v_mov_b32_e32 v65, v50
	v_mov_b32_e32 v50, v59
	v_mov_b32_e32 v59, v52
	v_mov_b32_e32 v52, v61
	v_mov_b32_e32 v82, v62
	v_mov_b32_e32 v62, v64
	v_mov_b32_e32 v64, v58
	v_mov_b32_e32 v58, v60
	v_add_u32_e32 v84, 0x90, v148
	v_mad_i64_i32 v[60:61], s[0:1], v100, s52, v[146:147]
	v_ashrrev_i32_e32 v85, 31, v84
	v_lshl_add_u64 v[60:61], v[60:61], 0, v[122:123]
	s_nop 0
	v_lshlrev_b64 v[68:69], 6, v[84:85]
	s_waitcnt vmcnt(4)
	v_pk_add_f32 v[218:219], v[202:203], v[206:207]
	v_pk_add_f32 v[220:221], v[200:201], v[204:205]
	v_pk_add_f32 v[222:223], v[210:211], v[214:215]
	v_pk_add_f32 v[224:225], v[208:209], v[212:213]
	v_pk_add_f32 v[218:219], v[218:219], v[222:223]
	v_pk_add_f32 v[220:221], v[220:221], v[224:225]
	s_nop 0
	v_pk_mov_b32 v[222:223], v[220:221], v[218:219] op_sel:[1,0]
	v_mov_b32_e32 v221, v219
	v_pk_add_f32 v[220:221], v[222:223], v[220:221]
	s_nop 0
	v_add_f32_e32 v230, v220, v221
	v_mov_b32_e32 v231, v230
	s_nop 1
	v_permlane16_swap_b32_e32 v230, v231
	v_mov_b32_e32 v232, v230
	v_mov_b32_e32 v233, v231
	s_nop 1
	v_permlane32_swap_b32_e32 v230, v232
	v_permlane32_swap_b32_e32 v231, v233
	v_mov_b32_e32 v66, v230
	v_fmamk_f32 v66, v66, 0x3a800000, v158
	v_rsq_f32_e32 v66, v66
	v_lshl_add_u64 v[68:69], s[12:13], 0, v[68:69]
	v_pk_mul_f32 v[52:53], v[52:53], v[66:67] op_sel_hi:[1,0]
	v_pk_mul_f32 v[70:71], v[82:83], v[66:67] op_sel_hi:[1,0]
	v_pk_mul_f32 v[54:55], v[54:55], v[66:67] op_sel_hi:[1,0]
	v_pk_mul_f32 v[62:63], v[62:63], v[66:67] op_sel_hi:[1,0]
	v_pk_mul_f32 v[56:57], v[56:57], v[66:67] op_sel_hi:[1,0]
	v_pk_mul_f32 v[64:65], v[64:65], v[66:67] op_sel_hi:[1,0]
	v_pk_mul_f32 v[50:51], v[50:51], v[66:67] op_sel_hi:[1,0]
	v_pk_mul_f32 v[58:59], v[58:59], v[66:67] op_sel_hi:[1,0]
	v_mul_f32_e32 v77, 0xbfb8aa3b, v53
	v_mul_f32_e32 v66, 0xbfb8aa3b, v71
	v_mul_f32_e32 v67, 0xbfb8aa3b, v55
	v_mul_f32_e32 v72, 0xbfb8aa3b, v63
	v_mul_f32_e32 v73, 0xbfb8aa3b, v57
	v_mul_f32_e32 v74, 0xbfb8aa3b, v65
	v_mul_f32_e32 v75, 0xbfb8aa3b, v51
	v_mul_f32_e32 v76, 0xbfb8aa3b, v59
	v_exp_f32_e32 v77, v77
	v_exp_f32_e32 v66, v66
	v_exp_f32_e32 v67, v67
	v_exp_f32_e32 v72, v72
	v_exp_f32_e32 v73, v73
	v_exp_f32_e32 v74, v74
	v_exp_f32_e32 v75, v75
	v_exp_f32_e32 v76, v76
	v_add_f32_e32 v77, 1.0, v77
	v_add_f32_e32 v66, 1.0, v66
	v_add_f32_e32 v67, 1.0, v67
	v_add_f32_e32 v72, 1.0, v72
	v_add_f32_e32 v73, 1.0, v73
	v_add_f32_e32 v74, 1.0, v74
	v_add_f32_e32 v75, 1.0, v75
	v_add_f32_e32 v76, 1.0, v76
	v_rcp_f32_e32 v77, v77
	v_rcp_f32_e32 v66, v66
	v_rcp_f32_e32 v67, v67
	v_rcp_f32_e32 v72, v72
	v_rcp_f32_e32 v73, v73
	v_rcp_f32_e32 v74, v74
	v_rcp_f32_e32 v75, v75
	v_rcp_f32_e32 v76, v76
	v_mul_f32_e32 v53, v53, v77
	v_mul_f32_e32 v66, v71, v66
	v_mul_f32_e32 v55, v55, v67
	v_mul_f32_e32 v63, v63, v72
	v_mul_f32_e32 v57, v57, v73
	v_mul_f32_e32 v65, v65, v74
	v_mul_f32_e32 v51, v51, v75
	v_mul_f32_e32 v59, v59, v76
	v_mul_f32_e32 v53, v52, v53
	v_mul_f32_e32 v66, v70, v66
	v_mul_f32_e32 v54, v54, v55
	v_mul_f32_e32 v55, v62, v63
	v_mul_f32_e32 v56, v56, v57
	v_mul_f32_e32 v57, v64, v65
	v_mul_f32_e32 v62, v50, v51
	v_mul_f32_e32 v58, v58, v59
	v_cvt_pk_bf16_f32 v50, v66, v54
	v_cvt_pk_bf16_f32 v51, v55, v56
	v_cvt_pk_bf16_f32 v52, v57, v62
	v_cvt_pk_bf16_f32 v53, v58, v53
	global_store_dwordx4 v[60:61], v[50:53], off
	s_nop 0
	v_mov_b32_e32 v67, v38
	v_mov_b32_e32 v38, v47
	v_mov_b32_e32 v47, v40
	v_mov_b32_e32 v40, v49
	v_mov_b32_e32 v49, v34
	v_mov_b32_e32 v34, v43
	v_mov_b32_e32 v43, v36
	v_mov_b32_e32 v36, v45
	v_mov_b32_e32 v66, v46
	v_mov_b32_e32 v46, v48
	v_mov_b32_e32 v48, v42
	v_mov_b32_e32 v42, v44
	v_add_u32_e32 v68, 0xa0, v148
	v_mad_i64_i32 v[44:45], s[0:1], v84, s52, v[146:147]
	v_ashrrev_i32_e32 v69, 31, v68
	v_lshl_add_u64 v[44:45], v[44:45], 0, v[122:123]
	s_nop 0
	v_lshlrev_b64 v[52:53], 6, v[68:69]
	v_mov_b32_e32 v50, v231
	v_fmamk_f32 v50, v50, 0x3a800000, v158
	v_rsq_f32_e32 v50, v50
	v_lshl_add_u64 v[52:53], s[12:13], 0, v[52:53]
	v_pk_mul_f32 v[36:37], v[36:37], v[50:51] op_sel_hi:[1,0]
	v_pk_mul_f32 v[54:55], v[66:67], v[50:51] op_sel_hi:[1,0]
	v_pk_mul_f32 v[38:39], v[38:39], v[50:51] op_sel_hi:[1,0]
	v_pk_mul_f32 v[46:47], v[46:47], v[50:51] op_sel_hi:[1,0]
	v_pk_mul_f32 v[40:41], v[40:41], v[50:51] op_sel_hi:[1,0]
	v_pk_mul_f32 v[48:49], v[48:49], v[50:51] op_sel_hi:[1,0]
	v_pk_mul_f32 v[34:35], v[34:35], v[50:51] op_sel_hi:[1,0]
	v_pk_mul_f32 v[42:43], v[42:43], v[50:51] op_sel_hi:[1,0]
	v_mul_f32_e32 v61, 0xbfb8aa3b, v37
	v_mul_f32_e32 v50, 0xbfb8aa3b, v55
	v_mul_f32_e32 v51, 0xbfb8aa3b, v39
	v_mul_f32_e32 v56, 0xbfb8aa3b, v47
	v_mul_f32_e32 v57, 0xbfb8aa3b, v41
	v_mul_f32_e32 v58, 0xbfb8aa3b, v49
	v_mul_f32_e32 v59, 0xbfb8aa3b, v35
	v_mul_f32_e32 v60, 0xbfb8aa3b, v43
	v_exp_f32_e32 v61, v61
	v_exp_f32_e32 v50, v50
	v_exp_f32_e32 v51, v51
	v_exp_f32_e32 v56, v56
	v_exp_f32_e32 v57, v57
	v_exp_f32_e32 v58, v58
	v_exp_f32_e32 v59, v59
	v_exp_f32_e32 v60, v60
	v_add_f32_e32 v61, 1.0, v61
	v_add_f32_e32 v50, 1.0, v50
	v_add_f32_e32 v51, 1.0, v51
	v_add_f32_e32 v56, 1.0, v56
	v_add_f32_e32 v57, 1.0, v57
	v_add_f32_e32 v58, 1.0, v58
	v_add_f32_e32 v59, 1.0, v59
	v_add_f32_e32 v60, 1.0, v60
	v_rcp_f32_e32 v61, v61
	v_rcp_f32_e32 v50, v50
	v_rcp_f32_e32 v51, v51
	v_rcp_f32_e32 v56, v56
	v_rcp_f32_e32 v57, v57
	v_rcp_f32_e32 v58, v58
	v_rcp_f32_e32 v59, v59
	v_rcp_f32_e32 v60, v60
	v_mul_f32_e32 v37, v37, v61
	v_mul_f32_e32 v50, v55, v50
	v_mul_f32_e32 v39, v39, v51
	v_mul_f32_e32 v47, v47, v56
	v_mul_f32_e32 v41, v41, v57
	v_mul_f32_e32 v49, v49, v58
	v_mul_f32_e32 v35, v35, v59
	v_mul_f32_e32 v43, v43, v60
	v_mul_f32_e32 v37, v36, v37
	v_mul_f32_e32 v50, v54, v50
	v_mul_f32_e32 v38, v38, v39
	v_mul_f32_e32 v39, v46, v47
	v_mul_f32_e32 v40, v40, v41
	v_mul_f32_e32 v41, v48, v49
	v_mul_f32_e32 v46, v34, v35
	v_mul_f32_e32 v42, v42, v43
	v_cvt_pk_bf16_f32 v34, v50, v38
	v_cvt_pk_bf16_f32 v35, v39, v40
	v_cvt_pk_bf16_f32 v36, v41, v46
	v_cvt_pk_bf16_f32 v37, v42, v37
	global_store_dwordx4 v[44:45], v[34:37], off
	s_nop 0
	v_mov_b32_e32 v51, v22
	v_mov_b32_e32 v22, v31
	v_mov_b32_e32 v31, v24
	v_mov_b32_e32 v24, v33
	v_mov_b32_e32 v33, v18
	v_mov_b32_e32 v18, v27
	v_mov_b32_e32 v27, v20
	v_mov_b32_e32 v20, v29
	v_mov_b32_e32 v50, v30
	v_mov_b32_e32 v30, v32
	v_mov_b32_e32 v32, v26
	v_mov_b32_e32 v26, v28
	v_add_u32_e32 v52, 0xb0, v148
	v_mad_i64_i32 v[28:29], s[0:1], v68, s52, v[146:147]
	v_ashrrev_i32_e32 v53, 31, v52
	v_lshl_add_u64 v[28:29], v[28:29], 0, v[122:123]
	s_nop 0
	v_lshlrev_b64 v[36:37], 6, v[52:53]
	v_mov_b32_e32 v34, v232
	v_fmamk_f32 v34, v34, 0x3a800000, v158
	v_rsq_f32_e32 v34, v34
	v_lshl_add_u64 v[36:37], s[12:13], 0, v[36:37]
	v_pk_mul_f32 v[20:21], v[20:21], v[34:35] op_sel_hi:[1,0]
	v_pk_mul_f32 v[38:39], v[50:51], v[34:35] op_sel_hi:[1,0]
	v_pk_mul_f32 v[22:23], v[22:23], v[34:35] op_sel_hi:[1,0]
	v_pk_mul_f32 v[30:31], v[30:31], v[34:35] op_sel_hi:[1,0]
	v_pk_mul_f32 v[24:25], v[24:25], v[34:35] op_sel_hi:[1,0]
	v_pk_mul_f32 v[32:33], v[32:33], v[34:35] op_sel_hi:[1,0]
	v_pk_mul_f32 v[18:19], v[18:19], v[34:35] op_sel_hi:[1,0]
	v_pk_mul_f32 v[26:27], v[26:27], v[34:35] op_sel_hi:[1,0]
	v_mul_f32_e32 v45, 0xbfb8aa3b, v21
	v_mul_f32_e32 v34, 0xbfb8aa3b, v39
	v_mul_f32_e32 v35, 0xbfb8aa3b, v23
	v_mul_f32_e32 v40, 0xbfb8aa3b, v31
	v_mul_f32_e32 v41, 0xbfb8aa3b, v25
	v_mul_f32_e32 v42, 0xbfb8aa3b, v33
	v_mul_f32_e32 v43, 0xbfb8aa3b, v19
	v_mul_f32_e32 v44, 0xbfb8aa3b, v27
	v_exp_f32_e32 v45, v45
	v_exp_f32_e32 v34, v34
	v_exp_f32_e32 v35, v35
	v_exp_f32_e32 v40, v40
	v_exp_f32_e32 v41, v41
	v_exp_f32_e32 v42, v42
	v_exp_f32_e32 v43, v43
	v_exp_f32_e32 v44, v44
	v_add_f32_e32 v45, 1.0, v45
	v_add_f32_e32 v34, 1.0, v34
	v_add_f32_e32 v35, 1.0, v35
	v_add_f32_e32 v40, 1.0, v40
	v_add_f32_e32 v41, 1.0, v41
	v_add_f32_e32 v42, 1.0, v42
	v_add_f32_e32 v43, 1.0, v43
	v_add_f32_e32 v44, 1.0, v44
	v_rcp_f32_e32 v45, v45
	v_rcp_f32_e32 v34, v34
	v_rcp_f32_e32 v35, v35
	v_rcp_f32_e32 v40, v40
	v_rcp_f32_e32 v41, v41
	v_rcp_f32_e32 v42, v42
	v_rcp_f32_e32 v43, v43
	v_rcp_f32_e32 v44, v44
	v_mul_f32_e32 v21, v21, v45
	v_mul_f32_e32 v34, v39, v34
	v_mul_f32_e32 v23, v23, v35
	v_mul_f32_e32 v31, v31, v40
	v_mul_f32_e32 v25, v25, v41
	v_mul_f32_e32 v33, v33, v42
	v_mul_f32_e32 v19, v19, v43
	v_mul_f32_e32 v27, v27, v44
	v_mul_f32_e32 v21, v20, v21
	v_mul_f32_e32 v34, v38, v34
	v_mul_f32_e32 v22, v22, v23
	v_mul_f32_e32 v23, v30, v31
	v_mul_f32_e32 v24, v24, v25
	v_mul_f32_e32 v25, v32, v33
	v_mul_f32_e32 v30, v18, v19
	v_mul_f32_e32 v26, v26, v27
	v_cvt_pk_bf16_f32 v18, v34, v22
	v_cvt_pk_bf16_f32 v19, v23, v24
	v_cvt_pk_bf16_f32 v20, v25, v30
	v_cvt_pk_bf16_f32 v21, v26, v21
	global_store_dwordx4 v[28:29], v[18:21], off
	s_nop 0
	v_mov_b32_e32 v34, v14
	v_mov_b32_e32 v35, v10
	v_mov_b32_e32 v10, v15
	v_mov_b32_e32 v14, v16
	v_mov_b32_e32 v15, v12
	v_mov_b32_e32 v12, v17
	v_mov_b32_e32 v16, v6
	v_mov_b32_e32 v17, v2
	v_mov_b32_e32 v2, v7
	v_mov_b32_e32 v6, v8
	v_mov_b32_e32 v7, v4
	v_mov_b32_e32 v4, v9
	s_nop 0
	v_mad_i64_i32 v[18:19], s[0:1], v52, s52, v[146:147]
	v_mov_b32_e32 v8, v233
	v_fmamk_f32 v8, v8, 0x3a800000, v158
	v_rsq_f32_e32 v8, v8
	v_lshl_add_u64 v[18:19], v[18:19], 0, v[122:123]
	v_pk_mul_f32 v[4:5], v[4:5], v[8:9] op_sel_hi:[1,0]
	v_pk_mul_f32 v[20:21], v[34:35], v[8:9] op_sel_hi:[1,0]
	v_pk_mul_f32 v[10:11], v[10:11], v[8:9] op_sel_hi:[1,0]
	v_pk_mul_f32 v[14:15], v[14:15], v[8:9] op_sel_hi:[1,0]
	v_pk_mul_f32 v[12:13], v[12:13], v[8:9] op_sel_hi:[1,0]
	v_pk_mul_f32 v[16:17], v[16:17], v[8:9] op_sel_hi:[1,0]
	v_pk_mul_f32 v[2:3], v[2:3], v[8:9] op_sel_hi:[1,0]
	v_pk_mul_f32 v[6:7], v[6:7], v[8:9] op_sel_hi:[1,0]
	v_mul_f32_e32 v27, 0xbfb8aa3b, v5
	v_mul_f32_e32 v8, 0xbfb8aa3b, v21
	v_mul_f32_e32 v9, 0xbfb8aa3b, v11
	v_mul_f32_e32 v22, 0xbfb8aa3b, v15
	v_mul_f32_e32 v23, 0xbfb8aa3b, v13
	v_mul_f32_e32 v24, 0xbfb8aa3b, v17
	v_mul_f32_e32 v25, 0xbfb8aa3b, v3
	v_mul_f32_e32 v26, 0xbfb8aa3b, v7
	v_exp_f32_e32 v27, v27
	v_exp_f32_e32 v8, v8
	v_exp_f32_e32 v9, v9
	v_exp_f32_e32 v22, v22
	v_exp_f32_e32 v23, v23
	v_exp_f32_e32 v24, v24
	v_exp_f32_e32 v25, v25
	v_exp_f32_e32 v26, v26
	v_add_f32_e32 v27, 1.0, v27
	v_add_f32_e32 v8, 1.0, v8
	v_add_f32_e32 v9, 1.0, v9
	v_add_f32_e32 v22, 1.0, v22
	v_add_f32_e32 v23, 1.0, v23
	v_add_f32_e32 v24, 1.0, v24
	v_add_f32_e32 v25, 1.0, v25
	v_add_f32_e32 v26, 1.0, v26
	v_rcp_f32_e32 v27, v27
	v_rcp_f32_e32 v8, v8
	v_rcp_f32_e32 v9, v9
	v_rcp_f32_e32 v22, v22
	v_rcp_f32_e32 v23, v23
	v_rcp_f32_e32 v24, v24
	v_rcp_f32_e32 v25, v25
	v_rcp_f32_e32 v26, v26
	v_mul_f32_e32 v5, v5, v27
	v_mul_f32_e32 v8, v21, v8
	v_mul_f32_e32 v9, v11, v9
	v_mul_f32_e32 v11, v15, v22
	v_mul_f32_e32 v13, v13, v23
	v_mul_f32_e32 v15, v17, v24
	v_mul_f32_e32 v3, v3, v25
	v_mul_f32_e32 v7, v7, v26
	v_mul_f32_e32 v5, v4, v5
	v_mul_f32_e32 v8, v20, v8
	v_mul_f32_e32 v9, v10, v9
	v_mul_f32_e32 v10, v14, v11
	v_mul_f32_e32 v11, v12, v13
	v_mul_f32_e32 v12, v16, v15
	v_mul_f32_e32 v13, v2, v3
	v_mul_f32_e32 v6, v6, v7
	v_cvt_pk_bf16_f32 v2, v8, v9
	v_cvt_pk_bf16_f32 v3, v10, v11
	v_cvt_pk_bf16_f32 v4, v12, v13
	v_cvt_pk_bf16_f32 v5, v6, v5
	global_store_dwordx4 v[18:19], v[2:5], off
	s_cbranch_vccnz .LBB0_1356
	s_andn2_b64 vcc, exec, s[6:7]
	s_cbranch_vccnz .LBB0_1355
	s_barrier
	s_branch .LBB0_1355
